# attention: running-max reference moves only when a tile's row max exceeds it by more than 2^8 (deferred rescaling), so most K tiles skip the accumulator rescale
# baseline (speedup 1.0000x reference)
.Lattn_nopf:
	v_lshl_add_u64 v[130:131], s[86:87], 0, v[170:171]
	v_add_co_u32_e32 v132, vcc, s88, v130
	s_nop 1
	v_addc_co_u32_e32 v133, vcc, 0, v131, vcc
	v_add_co_u32_e32 v130, vcc, s17, v130
	global_load_dwordx4 v[158:161], v[132:133], off offset:512
	global_load_dwordx4 v[154:157], v[132:133], off offset:1024
	global_load_dwordx4 v[150:153], v[132:133], off offset:2560
	global_load_dwordx4 v[146:149], v[132:133], off offset:3072
	v_addc_co_u32_e32 v131, vcc, 0, v131, vcc
	v_lshl_add_u64 v[132:133], s[86:87], 0, v[168:169]
	v_add_co_u32_e32 v132, vcc, 0xae6f000, v132
	s_nop 1
	v_addc_co_u32_e32 v133, vcc, 0, v133, vcc
	global_load_dwordx4 v[138:141], v[130:131], off offset:512
	global_load_dwordx4 v[134:137], v[130:131], off offset:2560
	global_load_dwordx4 v[142:145], v[132:133], off offset:512
	s_nop 0
	global_load_dwordx4 v[130:133], v[132:133], off offset:2560
	v_mov_b32_e32 v188, s8
	ds_read_b32 v190, v188 offset:1024
	s_cmp_lt_u32 s9, 6
	s_cbranch_scc0 .Lattn_far_p
	s_waitcnt vmcnt(8)
	v_subrev_u32_e32 v188, 64, v177
	v_xor_b32_e32 v198, 32, v179
	v_lshlrev_b32_e32 v198, 2, v198
	v_max3_f32 v231, v98, v99, v100
	v_max3_f32 v231, v231, v101, v102
	v_max3_f32 v231, v231, v103, v104
	v_max3_f32 v231, v231, v105, v106
	v_max3_f32 v231, v231, v107, v108
	v_max3_f32 v231, v231, v109, v110
	v_max3_f32 v231, v231, v111, v112
	v_max3_f32 v231, v231, v113, v114
	v_max3_f32 v231, v231, v115, v116
	v_max3_f32 v231, v231, v117, v118
	v_max3_f32 v231, v231, v119, v120
	v_max3_f32 v231, v231, v121, v122
	v_max3_f32 v231, v231, v123, v124
	v_max3_f32 v231, v231, v125, v126
	v_max3_f32 v231, v231, v127, v128
	v_max_f32_e32 v231, v231, v129
	s_waitcnt lgkmcnt(0)
	v_fma_f32 v231, v231, v216, v190
	ds_bpermute_b32 v233, v198, v231
	v_max3_f32 v234, v66, v67, v68
	v_max3_f32 v234, v234, v69, v70
	v_max3_f32 v234, v234, v71, v72
	v_max3_f32 v234, v234, v73, v74
	v_max3_f32 v234, v234, v75, v76
	v_max3_f32 v234, v234, v77, v78
	v_max3_f32 v234, v234, v79, v80
	v_max3_f32 v234, v234, v81, v82
	v_max3_f32 v234, v234, v83, v84
	v_max3_f32 v234, v234, v85, v86
	v_max3_f32 v234, v234, v87, v88
	v_max3_f32 v234, v234, v89, v90
	v_max3_f32 v234, v234, v91, v92
	v_max3_f32 v234, v234, v93, v94
	v_max3_f32 v234, v234, v95, v96
	v_max_f32_e32 v234, v234, v97
	v_fma_f32 v234, v234, v216, v190
	ds_bpermute_b32 v235, v198, v234
	s_waitcnt lgkmcnt(1)
	v_max_f32_e32 v236, v231, v233
	v_sub_f32_e32 v226, v236, v199
	v_cmp_lt_f32_e32 vcc, 0x41000000, v226
	s_nop 1
	v_cndmask_b32_e32 v236, v199, v236, vcc
	v_sub_f32_e32 v226, v199, v236
	v_sub_f32_e32 v238, v190, v236
	v_sub_f32_e32 v239, v190, v236
	v_exp_f32_e32 v226, v226
	v_pk_fma_f32 v[98:99], v[98:99], v[216:217], v[238:239]
	v_pk_fma_f32 v[100:101], v[100:101], v[216:217], v[238:239]
	v_pk_fma_f32 v[102:103], v[102:103], v[216:217], v[238:239]
	v_pk_fma_f32 v[104:105], v[104:105], v[216:217], v[238:239]
	v_pk_fma_f32 v[106:107], v[106:107], v[216:217], v[238:239]
	v_pk_fma_f32 v[108:109], v[108:109], v[216:217], v[238:239]
	v_pk_fma_f32 v[110:111], v[110:111], v[216:217], v[238:239]
	v_pk_fma_f32 v[112:113], v[112:113], v[216:217], v[238:239]
	v_pk_fma_f32 v[114:115], v[114:115], v[216:217], v[238:239]
	v_pk_fma_f32 v[116:117], v[116:117], v[216:217], v[238:239]
	v_pk_fma_f32 v[118:119], v[118:119], v[216:217], v[238:239]
	v_pk_fma_f32 v[120:121], v[120:121], v[216:217], v[238:239]
	v_pk_fma_f32 v[122:123], v[122:123], v[216:217], v[238:239]
	v_pk_fma_f32 v[124:125], v[124:125], v[216:217], v[238:239]
	v_pk_fma_f32 v[126:127], v[126:127], v[216:217], v[238:239]
	v_pk_fma_f32 v[128:129], v[128:129], v[216:217], v[238:239]
	v_exp_f32_e32 v98, v98
	v_exp_f32_e32 v99, v99
	v_exp_f32_e32 v100, v100
	v_exp_f32_e32 v101, v101
	v_exp_f32_e32 v102, v102
	v_exp_f32_e32 v103, v103
	v_exp_f32_e32 v104, v104
	v_exp_f32_e32 v105, v105
	v_exp_f32_e32 v106, v106
	v_exp_f32_e32 v107, v107
	v_exp_f32_e32 v108, v108
	v_exp_f32_e32 v109, v109
	v_exp_f32_e32 v110, v110
	v_exp_f32_e32 v111, v111
	v_exp_f32_e32 v112, v112
	v_exp_f32_e32 v113, v113
	v_exp_f32_e32 v114, v114
	v_exp_f32_e32 v115, v115
	v_exp_f32_e32 v116, v116
	v_exp_f32_e32 v117, v117
	v_exp_f32_e32 v118, v118
	v_exp_f32_e32 v119, v119
	v_exp_f32_e32 v120, v120
	v_exp_f32_e32 v121, v121
	v_exp_f32_e32 v122, v122
	v_exp_f32_e32 v123, v123
	v_exp_f32_e32 v124, v124
	v_exp_f32_e32 v125, v125
	v_exp_f32_e32 v126, v126
	v_exp_f32_e32 v127, v127
	v_exp_f32_e32 v128, v128
	v_exp_f32_e32 v129, v129
	s_waitcnt lgkmcnt(0)
	v_max_f32_e32 v218, v234, v235
	v_sub_f32_e32 v228, v218, v189
	v_cmp_lt_f32_e32 vcc, 0x41000000, v228
	s_nop 1
	v_cndmask_b32_e32 v218, v189, v218, vcc
	v_sub_f32_e32 v228, v189, v218
	v_sub_f32_e32 v202, v190, v218
	v_sub_f32_e32 v203, v190, v218
	v_exp_f32_e32 v228, v228
	v_pk_fma_f32 v[66:67], v[66:67], v[216:217], v[202:203]
	v_pk_fma_f32 v[68:69], v[68:69], v[216:217], v[202:203]
	v_pk_fma_f32 v[70:71], v[70:71], v[216:217], v[202:203]
	v_pk_fma_f32 v[72:73], v[72:73], v[216:217], v[202:203]
	v_pk_fma_f32 v[74:75], v[74:75], v[216:217], v[202:203]
	v_pk_fma_f32 v[76:77], v[76:77], v[216:217], v[202:203]
	v_pk_fma_f32 v[78:79], v[78:79], v[216:217], v[202:203]
	v_pk_fma_f32 v[80:81], v[80:81], v[216:217], v[202:203]
	v_pk_fma_f32 v[82:83], v[82:83], v[216:217], v[202:203]
	v_pk_fma_f32 v[84:85], v[84:85], v[216:217], v[202:203]
	v_pk_fma_f32 v[86:87], v[86:87], v[216:217], v[202:203]
	v_pk_fma_f32 v[88:89], v[88:89], v[216:217], v[202:203]
	v_pk_fma_f32 v[90:91], v[90:91], v[216:217], v[202:203]
	v_pk_fma_f32 v[92:93], v[92:93], v[216:217], v[202:203]
	v_pk_fma_f32 v[94:95], v[94:95], v[216:217], v[202:203]
	v_pk_fma_f32 v[96:97], v[96:97], v[216:217], v[202:203]
	v_exp_f32_e32 v66, v66
	v_exp_f32_e32 v67, v67
	v_exp_f32_e32 v68, v68
	v_exp_f32_e32 v69, v69
	v_exp_f32_e32 v70, v70
	v_exp_f32_e32 v71, v71
	v_exp_f32_e32 v72, v72
	v_exp_f32_e32 v73, v73
	v_exp_f32_e32 v74, v74
	v_exp_f32_e32 v75, v75
	v_exp_f32_e32 v76, v76
	v_exp_f32_e32 v77, v77
	v_exp_f32_e32 v78, v78
	v_exp_f32_e32 v79, v79
	v_exp_f32_e32 v80, v80
	v_exp_f32_e32 v81, v81
	v_exp_f32_e32 v82, v82
	v_exp_f32_e32 v83, v83
	v_exp_f32_e32 v84, v84
	v_exp_f32_e32 v85, v85
	v_exp_f32_e32 v86, v86
	v_exp_f32_e32 v87, v87
	v_exp_f32_e32 v88, v88
	v_exp_f32_e32 v89, v89
	v_exp_f32_e32 v90, v90
	v_exp_f32_e32 v91, v91
	v_exp_f32_e32 v92, v92
	v_exp_f32_e32 v93, v93
	v_exp_f32_e32 v94, v94
	v_exp_f32_e32 v95, v95
	v_exp_f32_e32 v96, v96
	v_exp_f32_e32 v97, v97
	v_pk_add_f32 v[212:213], v[98:99], v[100:101]
	v_pk_add_f32 v[214:215], v[102:103], v[104:105]
	v_pk_add_f32 v[212:213], v[212:213], v[106:107]
	v_pk_add_f32 v[214:215], v[214:215], v[108:109]
	v_pk_add_f32 v[212:213], v[212:213], v[110:111]
	v_pk_add_f32 v[214:215], v[214:215], v[112:113]
	v_pk_add_f32 v[212:213], v[212:213], v[114:115]
	v_pk_add_f32 v[214:215], v[214:215], v[116:117]
	v_pk_add_f32 v[212:213], v[212:213], v[118:119]
	v_pk_add_f32 v[214:215], v[214:215], v[120:121]
	v_pk_add_f32 v[212:213], v[212:213], v[122:123]
	v_pk_add_f32 v[214:215], v[214:215], v[124:125]
	v_pk_add_f32 v[212:213], v[212:213], v[126:127]
	v_pk_add_f32 v[214:215], v[214:215], v[128:129]
	v_pk_add_f32 v[212:213], v[212:213], v[214:215]
	v_add_f32_e32 v210, v212, v213
	ds_bpermute_b32 v211, v198, v210
	v_pk_add_f32 v[220:221], v[66:67], v[68:69]
	v_pk_add_f32 v[222:223], v[70:71], v[72:73]
	v_pk_add_f32 v[220:221], v[220:221], v[74:75]
	v_pk_add_f32 v[222:223], v[222:223], v[76:77]
	v_pk_add_f32 v[220:221], v[220:221], v[78:79]
	v_pk_add_f32 v[222:223], v[222:223], v[80:81]
	v_pk_add_f32 v[220:221], v[220:221], v[82:83]
	v_pk_add_f32 v[222:223], v[222:223], v[84:85]
	v_pk_add_f32 v[220:221], v[220:221], v[86:87]
	v_pk_add_f32 v[222:223], v[222:223], v[88:89]
	v_pk_add_f32 v[220:221], v[220:221], v[90:91]
	v_pk_add_f32 v[222:223], v[222:223], v[92:93]
	v_pk_add_f32 v[220:221], v[220:221], v[94:95]
	v_pk_add_f32 v[222:223], v[222:223], v[96:97]
	v_pk_add_f32 v[220:221], v[220:221], v[222:223]
	v_add_f32_e32 v224, v220, v221
	ds_bpermute_b32 v225, v198, v224
	v_cmp_neq_f32_e32 vcc, 1.0, v226
	s_cbranch_vccz .Lattn_near_p_sa
	v_mov_b32_e32 v227, v226
	v_pk_mul_f32 v[64:65], v[64:65], v[226:227]
	v_pk_mul_f32 v[62:63], v[62:63], v[226:227]
	v_pk_mul_f32 v[60:61], v[60:61], v[226:227]
	v_pk_mul_f32 v[58:59], v[58:59], v[226:227]
	v_pk_mul_f32 v[56:57], v[56:57], v[226:227]
	v_pk_mul_f32 v[54:55], v[54:55], v[226:227]
	v_pk_mul_f32 v[52:53], v[52:53], v[226:227]
	v_pk_mul_f32 v[50:51], v[50:51], v[226:227]
	v_pk_mul_f32 v[48:49], v[48:49], v[226:227]
	v_pk_mul_f32 v[46:47], v[46:47], v[226:227]
	v_pk_mul_f32 v[44:45], v[44:45], v[226:227]
	v_pk_mul_f32 v[42:43], v[42:43], v[226:227]
	v_pk_mul_f32 v[40:41], v[40:41], v[226:227]
	v_pk_mul_f32 v[38:39], v[38:39], v[226:227]
	v_pk_mul_f32 v[36:37], v[36:37], v[226:227]
	v_pk_mul_f32 v[34:35], v[34:35], v[226:227]

.Lattn_far_p:
	s_waitcnt vmcnt(8)
	v_subrev_u32_e32 v188, 64, v177
	v_xor_b32_e32 v198, 32, v179
	v_lshlrev_b32_e32 v198, 2, v198
	v_lshl_add_u32 v191, v177, 2, s8
	s_add_i32 s2, s8, 0x200
	v_add_u32_e32 v192, 0xfffffff4, v191
	v_min_i32_e32 v192, s2, v192
	ds_read2_b32 v[200:201], v192 offset0:131 offset1:130
	ds_read2_b32 v[202:203], v192 offset0:129 offset1:128
	v_add_u32_e32 v193, 0xffffffd4, v191
	v_min_i32_e32 v193, s2, v193
	ds_read2_b32 v[204:205], v193 offset0:131 offset1:130
	ds_read2_b32 v[206:207], v193 offset0:129 offset1:128
	v_add_u32_e32 v192, 0xffffffb4, v191
	v_min_i32_e32 v192, s2, v192
	ds_read2_b32 v[208:209], v192 offset0:131 offset1:130
	ds_read2_b32 v[210:211], v192 offset0:129 offset1:128
	v_add_u32_e32 v193, 0xffffff94, v191
	v_min_i32_e32 v193, s2, v193
	ds_read2_b32 v[212:213], v193 offset0:131 offset1:130
	ds_read2_b32 v[214:215], v193 offset0:129 offset1:128
	v_add_u32_e32 v192, 0xffffff74, v191
	v_min_i32_e32 v192, s2, v192
	ds_read2_b32 v[218:219], v192 offset0:131 offset1:130
	ds_read2_b32 v[220:221], v192 offset0:129 offset1:128
	v_add_u32_e32 v193, 0xffffff54, v191
	v_min_i32_e32 v193, s2, v193
	ds_read2_b32 v[222:223], v193 offset0:131 offset1:130
	ds_read2_b32 v[224:225], v193 offset0:129 offset1:128
	v_add_u32_e32 v192, 0xffffff34, v191
	v_min_i32_e32 v192, s2, v192
	ds_read2_b32 v[226:227], v192 offset0:131 offset1:130
	ds_read2_b32 v[228:229], v192 offset0:129 offset1:128
	s_waitcnt lgkmcnt(6)
	v_pk_fma_f32 v[66:67], v[66:67], v[216:217], v[200:201]
	v_pk_fma_f32 v[68:69], v[68:69], v[216:217], v[202:203]
	v_pk_fma_f32 v[70:71], v[70:71], v[216:217], v[204:205]
	v_pk_fma_f32 v[72:73], v[72:73], v[216:217], v[206:207]
	v_pk_fma_f32 v[74:75], v[74:75], v[216:217], v[208:209]
	v_pk_fma_f32 v[76:77], v[76:77], v[216:217], v[210:211]
	v_pk_fma_f32 v[78:79], v[78:79], v[216:217], v[212:213]
	v_pk_fma_f32 v[80:81], v[80:81], v[216:217], v[214:215]
	v_add_u32_e32 v193, 0xffffff14, v191
	v_min_i32_e32 v193, s2, v193
	ds_read2_b32 v[230:231], v193 offset0:131 offset1:130
	ds_read2_b32 v[232:233], v193 offset0:129 offset1:128
	v_add_u32_e32 v192, 0xfffffef4, v191
	v_min_i32_e32 v192, s2, v192
	ds_read2_b32 v[200:201], v192 offset0:131 offset1:130
	ds_read2_b32 v[202:203], v192 offset0:129 offset1:128
	v_add_u32_e32 v193, 0xfffffed4, v191
	v_min_i32_e32 v193, s2, v193
	ds_read2_b32 v[204:205], v193 offset0:131 offset1:130
	ds_read2_b32 v[206:207], v193 offset0:129 offset1:128
	v_add_u32_e32 v192, 0xfffffeb4, v191
	v_min_i32_e32 v192, s2, v192
	ds_read2_b32 v[208:209], v192 offset0:131 offset1:130
	ds_read2_b32 v[210:211], v192 offset0:129 offset1:128
	s_waitcnt lgkmcnt(6)
	v_pk_fma_f32 v[98:99], v[98:99], v[216:217], v[218:219]
	v_pk_fma_f32 v[100:101], v[100:101], v[216:217], v[220:221]
	v_pk_fma_f32 v[102:103], v[102:103], v[216:217], v[222:223]
	v_pk_fma_f32 v[104:105], v[104:105], v[216:217], v[224:225]
	v_pk_fma_f32 v[106:107], v[106:107], v[216:217], v[226:227]
	v_pk_fma_f32 v[108:109], v[108:109], v[216:217], v[228:229]
	v_pk_fma_f32 v[110:111], v[110:111], v[216:217], v[230:231]
	v_pk_fma_f32 v[112:113], v[112:113], v[216:217], v[232:233]
	v_pk_fma_f32 v[82:83], v[82:83], v[216:217], v[218:219]
	v_pk_fma_f32 v[84:85], v[84:85], v[216:217], v[220:221]
	v_pk_fma_f32 v[86:87], v[86:87], v[216:217], v[222:223]
	v_pk_fma_f32 v[88:89], v[88:89], v[216:217], v[224:225]
	v_pk_fma_f32 v[90:91], v[90:91], v[216:217], v[226:227]
	v_pk_fma_f32 v[92:93], v[92:93], v[216:217], v[228:229]
	v_pk_fma_f32 v[94:95], v[94:95], v[216:217], v[230:231]
	v_pk_fma_f32 v[96:97], v[96:97], v[216:217], v[232:233]
	v_add_u32_e32 v193, 0xfffffe94, v191
	v_min_i32_e32 v193, s2, v193
	ds_read2_b32 v[212:213], v193 offset0:131 offset1:130
	ds_read2_b32 v[214:215], v193 offset0:129 offset1:128
	s_waitcnt lgkmcnt(0)
	v_pk_fma_f32 v[114:115], v[114:115], v[216:217], v[200:201]
	v_pk_fma_f32 v[116:117], v[116:117], v[216:217], v[202:203]
	v_pk_fma_f32 v[118:119], v[118:119], v[216:217], v[204:205]
	v_pk_fma_f32 v[120:121], v[120:121], v[216:217], v[206:207]
	v_pk_fma_f32 v[122:123], v[122:123], v[216:217], v[208:209]
	v_pk_fma_f32 v[124:125], v[124:125], v[216:217], v[210:211]
	v_pk_fma_f32 v[126:127], v[126:127], v[216:217], v[212:213]
	v_pk_fma_f32 v[128:129], v[128:129], v[216:217], v[214:215]
	v_max3_f32 v231, v98, v99, v100
	v_max3_f32 v231, v231, v101, v102
	v_max3_f32 v231, v231, v103, v104
	v_max3_f32 v231, v231, v105, v106
	v_max3_f32 v231, v231, v107, v108
	v_max3_f32 v231, v231, v109, v110
	v_max3_f32 v231, v231, v111, v112
	v_max3_f32 v231, v231, v113, v114
	v_max3_f32 v231, v231, v115, v116
	v_max3_f32 v231, v231, v117, v118
	v_max3_f32 v231, v231, v119, v120
	v_max3_f32 v231, v231, v121, v122
	v_max3_f32 v231, v231, v123, v124
	v_max3_f32 v231, v231, v125, v126
	v_max3_f32 v231, v231, v127, v128
	v_max_f32_e32 v231, v231, v129
	ds_bpermute_b32 v233, v198, v231
	v_max3_f32 v234, v66, v67, v68
	v_max3_f32 v234, v234, v69, v70
	v_max3_f32 v234, v234, v71, v72
	v_max3_f32 v234, v234, v73, v74
	v_max3_f32 v234, v234, v75, v76
	v_max3_f32 v234, v234, v77, v78
	v_max3_f32 v234, v234, v79, v80
	v_max3_f32 v234, v234, v81, v82
	v_max3_f32 v234, v234, v83, v84
	v_max3_f32 v234, v234, v85, v86
	v_max3_f32 v234, v234, v87, v88
	v_max3_f32 v234, v234, v89, v90
	v_max3_f32 v234, v234, v91, v92
	v_max3_f32 v234, v234, v93, v94
	v_max3_f32 v234, v234, v95, v96
	v_max_f32_e32 v234, v234, v97
	ds_bpermute_b32 v235, v198, v234
	s_waitcnt lgkmcnt(1)
	v_max_f32_e32 v236, v231, v233
	v_sub_f32_e32 v226, v236, v199
	v_cmp_lt_f32_e32 vcc, 0x41000000, v226
	s_nop 1
	v_cndmask_b32_e32 v236, v199, v236, vcc
	v_sub_f32_e32 v226, v199, v236
	v_sub_f32_e32 v238, 0, v236
	v_sub_f32_e32 v239, 0, v236
	v_exp_f32_e32 v226, v226
	v_pk_add_f32 v[98:99], v[98:99], v[238:239]
	v_pk_add_f32 v[100:101], v[100:101], v[238:239]
	v_pk_add_f32 v[102:103], v[102:103], v[238:239]
	v_pk_add_f32 v[104:105], v[104:105], v[238:239]
	v_pk_add_f32 v[106:107], v[106:107], v[238:239]
	v_pk_add_f32 v[108:109], v[108:109], v[238:239]
	v_pk_add_f32 v[110:111], v[110:111], v[238:239]
	v_pk_add_f32 v[112:113], v[112:113], v[238:239]
	v_pk_add_f32 v[114:115], v[114:115], v[238:239]
	v_pk_add_f32 v[116:117], v[116:117], v[238:239]
	v_pk_add_f32 v[118:119], v[118:119], v[238:239]
	v_pk_add_f32 v[120:121], v[120:121], v[238:239]
	v_pk_add_f32 v[122:123], v[122:123], v[238:239]
	v_pk_add_f32 v[124:125], v[124:125], v[238:239]
	v_pk_add_f32 v[126:127], v[126:127], v[238:239]
	v_pk_add_f32 v[128:129], v[128:129], v[238:239]
	v_exp_f32_e32 v98, v98
	v_exp_f32_e32 v99, v99
	v_exp_f32_e32 v100, v100
	v_exp_f32_e32 v101, v101
	v_exp_f32_e32 v102, v102
	v_exp_f32_e32 v103, v103
	v_exp_f32_e32 v104, v104
	v_exp_f32_e32 v105, v105
	v_exp_f32_e32 v106, v106
	v_exp_f32_e32 v107, v107
	v_exp_f32_e32 v108, v108
	v_exp_f32_e32 v109, v109
	v_exp_f32_e32 v110, v110
	v_exp_f32_e32 v111, v111
	v_exp_f32_e32 v112, v112
	v_exp_f32_e32 v113, v113
	v_exp_f32_e32 v114, v114
	v_exp_f32_e32 v115, v115
	v_exp_f32_e32 v116, v116
	v_exp_f32_e32 v117, v117
	v_exp_f32_e32 v118, v118
	v_exp_f32_e32 v119, v119
	v_exp_f32_e32 v120, v120
	v_exp_f32_e32 v121, v121
	v_exp_f32_e32 v122, v122
	v_exp_f32_e32 v123, v123
	v_exp_f32_e32 v124, v124
	v_exp_f32_e32 v125, v125
	v_exp_f32_e32 v126, v126
	v_exp_f32_e32 v127, v127
	v_exp_f32_e32 v128, v128
	v_exp_f32_e32 v129, v129
	s_waitcnt lgkmcnt(0)
	v_max_f32_e32 v218, v234, v235
	v_sub_f32_e32 v228, v218, v189
	v_cmp_lt_f32_e32 vcc, 0x41000000, v228
	s_nop 1
	v_cndmask_b32_e32 v218, v189, v218, vcc
	v_sub_f32_e32 v228, v189, v218
	v_sub_f32_e32 v202, 0, v218
	v_sub_f32_e32 v203, 0, v218
	v_exp_f32_e32 v228, v228
	v_pk_add_f32 v[66:67], v[66:67], v[202:203]
	v_pk_add_f32 v[68:69], v[68:69], v[202:203]
	v_pk_add_f32 v[70:71], v[70:71], v[202:203]
	v_pk_add_f32 v[72:73], v[72:73], v[202:203]
	v_pk_add_f32 v[74:75], v[74:75], v[202:203]
	v_pk_add_f32 v[76:77], v[76:77], v[202:203]
	v_pk_add_f32 v[78:79], v[78:79], v[202:203]
	v_pk_add_f32 v[80:81], v[80:81], v[202:203]
	v_pk_add_f32 v[82:83], v[82:83], v[202:203]
	v_pk_add_f32 v[84:85], v[84:85], v[202:203]
	v_pk_add_f32 v[86:87], v[86:87], v[202:203]
	v_pk_add_f32 v[88:89], v[88:89], v[202:203]
	v_pk_add_f32 v[90:91], v[90:91], v[202:203]
	v_pk_add_f32 v[92:93], v[92:93], v[202:203]
	v_pk_add_f32 v[94:95], v[94:95], v[202:203]
	v_pk_add_f32 v[96:97], v[96:97], v[202:203]
	v_exp_f32_e32 v66, v66
	v_exp_f32_e32 v67, v67
	v_exp_f32_e32 v68, v68
	v_exp_f32_e32 v69, v69
	v_exp_f32_e32 v70, v70
	v_exp_f32_e32 v71, v71
	v_exp_f32_e32 v72, v72
	v_exp_f32_e32 v73, v73
	v_exp_f32_e32 v74, v74
	v_exp_f32_e32 v75, v75
	v_exp_f32_e32 v76, v76
	v_exp_f32_e32 v77, v77
	v_exp_f32_e32 v78, v78
	v_exp_f32_e32 v79, v79
	v_exp_f32_e32 v80, v80
	v_exp_f32_e32 v81, v81
	v_exp_f32_e32 v82, v82
	v_exp_f32_e32 v83, v83
	v_exp_f32_e32 v84, v84
	v_exp_f32_e32 v85, v85
	v_exp_f32_e32 v86, v86
	v_exp_f32_e32 v87, v87
	v_exp_f32_e32 v88, v88
	v_exp_f32_e32 v89, v89
	v_exp_f32_e32 v90, v90
	v_exp_f32_e32 v91, v91
	v_exp_f32_e32 v92, v92
	v_exp_f32_e32 v93, v93
	v_exp_f32_e32 v94, v94
	v_exp_f32_e32 v95, v95
	v_exp_f32_e32 v96, v96
	v_exp_f32_e32 v97, v97
	v_pk_add_f32 v[212:213], v[98:99], v[100:101]
	v_pk_add_f32 v[214:215], v[102:103], v[104:105]
	v_pk_add_f32 v[212:213], v[212:213], v[106:107]
	v_pk_add_f32 v[214:215], v[214:215], v[108:109]
	v_pk_add_f32 v[212:213], v[212:213], v[110:111]
	v_pk_add_f32 v[214:215], v[214:215], v[112:113]
	v_pk_add_f32 v[212:213], v[212:213], v[114:115]
	v_pk_add_f32 v[214:215], v[214:215], v[116:117]
	v_pk_add_f32 v[212:213], v[212:213], v[118:119]
	v_pk_add_f32 v[214:215], v[214:215], v[120:121]
	v_pk_add_f32 v[212:213], v[212:213], v[122:123]
	v_pk_add_f32 v[214:215], v[214:215], v[124:125]
	v_pk_add_f32 v[212:213], v[212:213], v[126:127]
	v_pk_add_f32 v[214:215], v[214:215], v[128:129]
	v_pk_add_f32 v[212:213], v[212:213], v[214:215]
	v_add_f32_e32 v210, v212, v213
	ds_bpermute_b32 v211, v198, v210
	v_pk_add_f32 v[220:221], v[66:67], v[68:69]
	v_pk_add_f32 v[222:223], v[70:71], v[72:73]
	v_pk_add_f32 v[220:221], v[220:221], v[74:75]
	v_pk_add_f32 v[222:223], v[222:223], v[76:77]
	v_pk_add_f32 v[220:221], v[220:221], v[78:79]
	v_pk_add_f32 v[222:223], v[222:223], v[80:81]
	v_pk_add_f32 v[220:221], v[220:221], v[82:83]
	v_pk_add_f32 v[222:223], v[222:223], v[84:85]
	v_pk_add_f32 v[220:221], v[220:221], v[86:87]
	v_pk_add_f32 v[222:223], v[222:223], v[88:89]
	v_pk_add_f32 v[220:221], v[220:221], v[90:91]
	v_pk_add_f32 v[222:223], v[222:223], v[92:93]
	v_pk_add_f32 v[220:221], v[220:221], v[94:95]
	v_pk_add_f32 v[222:223], v[222:223], v[96:97]
	v_pk_add_f32 v[220:221], v[220:221], v[222:223]
	v_add_f32_e32 v224, v220, v221
	ds_bpermute_b32 v225, v198, v224
	v_cmp_neq_f32_e32 vcc, 1.0, v226
	s_cbranch_vccz .Lattn_far_p_sa
	v_mov_b32_e32 v227, v226
	v_pk_mul_f32 v[64:65], v[64:65], v[226:227]
	v_pk_mul_f32 v[62:63], v[62:63], v[226:227]
	v_pk_mul_f32 v[60:61], v[60:61], v[226:227]
	v_pk_mul_f32 v[58:59], v[58:59], v[226:227]
	v_pk_mul_f32 v[56:57], v[56:57], v[226:227]
	v_pk_mul_f32 v[54:55], v[54:55], v[226:227]
	v_pk_mul_f32 v[52:53], v[52:53], v[226:227]
	v_pk_mul_f32 v[50:51], v[50:51], v[226:227]
	v_pk_mul_f32 v[48:49], v[48:49], v[226:227]
	v_pk_mul_f32 v[46:47], v[46:47], v[226:227]
	v_pk_mul_f32 v[44:45], v[44:45], v[226:227]
	v_pk_mul_f32 v[42:43], v[42:43], v[226:227]
	v_pk_mul_f32 v[40:41], v[40:41], v[226:227]
	v_pk_mul_f32 v[38:39], v[38:39], v[226:227]
	v_pk_mul_f32 v[36:37], v[36:37], v[226:227]
	v_pk_mul_f32 v[34:35], v[34:35], v[226:227]
